# GEMM k-loop: LDS-DMA issue moved to top of k-step, interleaved with first-half LDS reads
# speedup vs baseline: 1.0261x; 1.0055x over previous
.LBB0_226:
	s_and_b32 s0, s19, 0x2000
	s_xor_b32 s1, s0, 0x2000
	s_lshl_b32 s0, s0, 1
	v_add_u32_e32 v0, s0, v151
	v_add_u32_e32 v159, s0, v152
	v_add_u32_e32 v126, v0, v157
	v_add_u32_e32 v164, v159, v157
	s_lshl_b32 s1, s1, 1
	v_readfirstlane_b32 s0, v250
	s_nop 0
	s_add_u32 m0, s0, s1
	ds_read_b128 v[82:85], v126
	global_load_lds_dwordx4 v246, s[98:99]
	s_add_u32 m0, m0, 0x8000
	ds_read_b128 v[86:89], v126 offset:2048
	global_load_lds_dwordx4 v246, s[100:101]
	s_add_u32 m0, m0, 0xffff8400
	ds_read_b128 v[122:125], v126 offset:4096
	global_load_lds_dwordx4 v247, s[98:99]
	s_add_u32 m0, m0, 0x8000
	ds_read_b128 v[126:129], v126 offset:6144
	global_load_lds_dwordx4 v247, s[100:101]
	s_add_u32 m0, m0, 0xffff8400
	ds_read_b128 v[130:133], v164 offset:32768
	global_load_lds_dwordx4 v248, s[98:99]
	s_add_u32 m0, m0, 0x8000
	ds_read_b128 v[134:137], v164 offset:34816
	global_load_lds_dwordx4 v248, s[100:101]
	s_add_u32 m0, m0, 0xffff8400
	ds_read_b128 v[160:163], v164 offset:36864
	global_load_lds_dwordx4 v249, s[98:99]
	s_add_u32 m0, m0, 0x8000
	ds_read_b128 v[164:167], v164 offset:38912
	global_load_lds_dwordx4 v249, s[100:101]
	v_add_u32_e32 v0, v0, v158
	ds_read_b128 v[214:217], v0
	ds_read_b128 v[218:221], v0 offset:2048
	ds_read_b128 v[222:225], v0 offset:4096
	ds_read_b128 v[226:229], v0 offset:6144
	v_add_u32_e32 v0, v159, v158
	ds_read_b128 v[230:233], v0 offset:32768
	ds_read_b128 v[234:237], v0 offset:34816
	ds_read_b128 v[238:241], v0 offset:36864
	s_setprio 1
	s_waitcnt lgkmcnt(7)
	ds_read_b128 v[242:245], v0 offset:38912
	s_add_u32 s98, s98, 0x80
	s_addc_u32 s99, s99, 0
	s_add_u32 s100, s100, 0x80
	s_addc_u32 s101, s101, 0
	v_mfma_f32_16x16x32_bf16 v[2:5], v[130:133], v[82:85], v[2:5]
	v_mfma_f32_16x16x32_bf16 v[6:9], v[134:137], v[82:85], v[6:9]
	v_mfma_f32_16x16x32_bf16 v[10:13], v[160:163], v[82:85], v[10:13]
	v_mfma_f32_16x16x32_bf16 v[14:17], v[164:167], v[82:85], v[14:17]
	v_mfma_f32_16x16x32_bf16 v[18:21], v[130:133], v[86:89], v[18:21]
	v_mfma_f32_16x16x32_bf16 v[22:25], v[134:137], v[86:89], v[22:25]
	v_mfma_f32_16x16x32_bf16 v[26:29], v[160:163], v[86:89], v[26:29]
	v_mfma_f32_16x16x32_bf16 v[30:33], v[164:167], v[86:89], v[30:33]
	v_mfma_f32_16x16x32_bf16 v[34:37], v[130:133], v[122:125], v[34:37]
	v_mfma_f32_16x16x32_bf16 v[38:41], v[134:137], v[122:125], v[38:41]
	v_mfma_f32_16x16x32_bf16 v[42:45], v[160:163], v[122:125], v[42:45]
	v_mfma_f32_16x16x32_bf16 v[46:49], v[164:167], v[122:125], v[46:49]
	v_mfma_f32_16x16x32_bf16 v[50:53], v[130:133], v[126:129], v[50:53]
	v_mfma_f32_16x16x32_bf16 v[54:57], v[134:137], v[126:129], v[54:57]
	v_mfma_f32_16x16x32_bf16 v[58:61], v[160:163], v[126:129], v[58:61]
	v_mfma_f32_16x16x32_bf16 v[62:65], v[164:167], v[126:129], v[62:65]
	s_waitcnt lgkmcnt(0)
	v_mfma_f32_16x16x32_bf16 v[2:5], v[230:233], v[214:217], v[2:5]
	v_mfma_f32_16x16x32_bf16 v[6:9], v[234:237], v[214:217], v[6:9]
	v_mfma_f32_16x16x32_bf16 v[10:13], v[238:241], v[214:217], v[10:13]
	v_mfma_f32_16x16x32_bf16 v[14:17], v[242:245], v[214:217], v[14:17]
	v_mfma_f32_16x16x32_bf16 v[18:21], v[230:233], v[218:221], v[18:21]
	v_mfma_f32_16x16x32_bf16 v[22:25], v[234:237], v[218:221], v[22:25]
	v_mfma_f32_16x16x32_bf16 v[26:29], v[238:241], v[218:221], v[26:29]
	v_mfma_f32_16x16x32_bf16 v[30:33], v[242:245], v[218:221], v[30:33]
	v_mfma_f32_16x16x32_bf16 v[34:37], v[230:233], v[222:225], v[34:37]
	v_mfma_f32_16x16x32_bf16 v[38:41], v[234:237], v[222:225], v[38:41]
	v_mfma_f32_16x16x32_bf16 v[42:45], v[238:241], v[222:225], v[42:45]
	v_mfma_f32_16x16x32_bf16 v[46:49], v[242:245], v[222:225], v[46:49]
	v_mfma_f32_16x16x32_bf16 v[50:53], v[230:233], v[226:229], v[50:53]
	v_mfma_f32_16x16x32_bf16 v[54:57], v[234:237], v[226:229], v[54:57]
	v_mfma_f32_16x16x32_bf16 v[58:61], v[238:241], v[226:229], v[58:61]
	v_mfma_f32_16x16x32_bf16 v[62:65], v[242:245], v[226:229], v[62:65]
	s_setprio 0
	s_addk_i32 s19, 0x2000
	s_waitcnt vmcnt(0)
	s_add_u32 s44, s44, 0x80
	s_addc_u32 s45, s45, 0
	s_cmpk_eq_i32 s44, 0x780
	s_waitcnt vmcnt(0)
	s_barrier
	s_cbranch_scc0 .LBB0_226
	s_andn2_b64 vcc, exec, s[42:43]
	s_cbranch_vccnz .LBB0_229
	v_lshl_add_u64 v[66:67], v[90:91], 0, s[46:47]
	v_readfirstlane_b32 s0, v138
	v_lshl_add_u64 v[68:69], v[66:67], 0, v[114:115]
	v_lshl_add_u64 v[74:75], v[92:93], 0, s[52:53]
	s_mov_b32 m0, s0
	v_readfirstlane_b32 s0, v139
	v_lshl_add_u64 v[76:77], v[74:75], 0, v[120:121]
	v_lshl_add_u64 v[78:79], v[74:75], 0, v[118:119]
	v_lshl_add_u64 v[80:81], v[74:75], 0, v[116:117]
	v_lshl_add_u64 v[74:75], v[74:75], 0, v[114:115]
	global_load_lds_dwordx4 v[68:69], off
	s_mov_b32 m0, s0
	v_readfirstlane_b32 s0, v140
	v_lshl_add_u64 v[70:71], v[66:67], 0, v[116:117]
	global_load_lds_dwordx4 v[74:75], off
	s_mov_b32 m0, s0
	v_readfirstlane_b32 s0, v141
	global_load_lds_dwordx4 v[70:71], off
	s_mov_b32 m0, s0
	v_readfirstlane_b32 s0, v142
	v_lshl_add_u64 v[72:73], v[66:67], 0, v[118:119]
	global_load_lds_dwordx4 v[80:81], off
	s_mov_b32 m0, s0
	v_readfirstlane_b32 s0, v143
	global_load_lds_dwordx4 v[72:73], off
	s_mov_b32 m0, s0
	v_readfirstlane_b32 s0, v144
	v_lshl_add_u64 v[66:67], v[66:67], 0, v[120:121]
	global_load_lds_dwordx4 v[78:79], off
	s_mov_b32 m0, s0
	v_readfirstlane_b32 s0, v145
	global_load_lds_dwordx4 v[66:67], off
	s_mov_b32 m0, s0
	s_nop 0
	global_load_lds_dwordx4 v[76:77], off

.LBB0_892:
	s_and_b32 s0, s19, 0x2000
	s_xor_b32 s1, s0, 0x2000
	s_lshl_b32 s0, s0, 1
	v_add_u32_e32 v95, s0, v125
	v_add_u32_e32 v162, s0, v126
	v_add_u32_e32 v142, v95, v128
	v_add_u32_e32 v158, v162, v128
	s_lshl_b32 s1, s1, 1
	v_readfirstlane_b32 s0, v250
	s_nop 0
	s_add_u32 m0, s0, s1
	ds_read_b128 v[130:133], v142
	global_load_lds_dwordx4 v246, s[98:99]
	s_add_u32 m0, m0, 0x8000
	ds_read_b128 v[134:137], v142 offset:2048
	global_load_lds_dwordx4 v246, s[100:101]
	s_add_u32 m0, m0, 0xffff8400
	ds_read_b128 v[138:141], v142 offset:4096
	global_load_lds_dwordx4 v247, s[98:99]
	s_add_u32 m0, m0, 0x8000
	ds_read_b128 v[142:145], v142 offset:6144
	global_load_lds_dwordx4 v247, s[100:101]
	s_add_u32 m0, m0, 0xffff8400
	ds_read_b128 v[146:149], v158 offset:32768
	global_load_lds_dwordx4 v248, s[98:99]
	s_add_u32 m0, m0, 0x8000
	ds_read_b128 v[150:153], v158 offset:34816
	global_load_lds_dwordx4 v248, s[100:101]
	s_add_u32 m0, m0, 0xffff8400
	ds_read_b128 v[154:157], v158 offset:36864
	global_load_lds_dwordx4 v249, s[98:99]
	s_add_u32 m0, m0, 0x8000
	ds_read_b128 v[158:161], v158 offset:38912
	global_load_lds_dwordx4 v249, s[100:101]
	v_add_u32_e32 v95, v95, v129
	ds_read_b128 v[214:217], v95
	ds_read_b128 v[218:221], v95 offset:2048
	ds_read_b128 v[222:225], v95 offset:4096
	ds_read_b128 v[226:229], v95 offset:6144
	v_add_u32_e32 v95, v162, v129
	ds_read_b128 v[230:233], v95 offset:32768
	ds_read_b128 v[234:237], v95 offset:34816
	ds_read_b128 v[238:241], v95 offset:36864
	s_setprio 1
	s_waitcnt lgkmcnt(7)
	ds_read_b128 v[242:245], v95 offset:38912
	s_add_u32 s98, s98, 0x80
	s_addc_u32 s99, s99, 0
	s_add_u32 s100, s100, 0x80
	s_addc_u32 s101, s101, 0
	v_mfma_f32_16x16x32_bf16 v[2:5], v[146:149], v[130:133], v[2:5]
	v_mfma_f32_16x16x32_bf16 v[6:9], v[150:153], v[130:133], v[6:9]
	v_mfma_f32_16x16x32_bf16 v[10:13], v[154:157], v[130:133], v[10:13]
	v_mfma_f32_16x16x32_bf16 v[14:17], v[158:161], v[130:133], v[14:17]
	v_mfma_f32_16x16x32_bf16 v[18:21], v[146:149], v[134:137], v[18:21]
	v_mfma_f32_16x16x32_bf16 v[22:25], v[150:153], v[134:137], v[22:25]
	v_mfma_f32_16x16x32_bf16 v[26:29], v[154:157], v[134:137], v[26:29]
	v_mfma_f32_16x16x32_bf16 v[30:33], v[158:161], v[134:137], v[30:33]
	v_mfma_f32_16x16x32_bf16 v[34:37], v[146:149], v[138:141], v[34:37]
	v_mfma_f32_16x16x32_bf16 v[38:41], v[150:153], v[138:141], v[38:41]
	v_mfma_f32_16x16x32_bf16 v[42:45], v[154:157], v[138:141], v[42:45]
	v_mfma_f32_16x16x32_bf16 v[46:49], v[158:161], v[138:141], v[46:49]
	v_mfma_f32_16x16x32_bf16 v[50:53], v[146:149], v[142:145], v[50:53]
	v_mfma_f32_16x16x32_bf16 v[54:57], v[150:153], v[142:145], v[54:57]
	v_mfma_f32_16x16x32_bf16 v[58:61], v[154:157], v[142:145], v[58:61]
	v_mfma_f32_16x16x32_bf16 v[62:65], v[158:161], v[142:145], v[62:65]
	s_waitcnt lgkmcnt(0)
	v_mfma_f32_16x16x32_bf16 v[2:5], v[230:233], v[214:217], v[2:5]
	v_mfma_f32_16x16x32_bf16 v[6:9], v[234:237], v[214:217], v[6:9]
	v_mfma_f32_16x16x32_bf16 v[10:13], v[238:241], v[214:217], v[10:13]
	v_mfma_f32_16x16x32_bf16 v[14:17], v[242:245], v[214:217], v[14:17]
	v_mfma_f32_16x16x32_bf16 v[18:21], v[230:233], v[218:221], v[18:21]
	v_mfma_f32_16x16x32_bf16 v[22:25], v[234:237], v[218:221], v[22:25]
	v_mfma_f32_16x16x32_bf16 v[26:29], v[238:241], v[218:221], v[26:29]
	v_mfma_f32_16x16x32_bf16 v[30:33], v[242:245], v[218:221], v[30:33]
	v_mfma_f32_16x16x32_bf16 v[34:37], v[230:233], v[222:225], v[34:37]
	v_mfma_f32_16x16x32_bf16 v[38:41], v[234:237], v[222:225], v[38:41]
	v_mfma_f32_16x16x32_bf16 v[42:45], v[238:241], v[222:225], v[42:45]
	v_mfma_f32_16x16x32_bf16 v[46:49], v[242:245], v[222:225], v[46:49]
	v_mfma_f32_16x16x32_bf16 v[50:53], v[230:233], v[226:229], v[50:53]
	v_mfma_f32_16x16x32_bf16 v[54:57], v[234:237], v[226:229], v[54:57]
	v_mfma_f32_16x16x32_bf16 v[58:61], v[238:241], v[226:229], v[58:61]
	v_mfma_f32_16x16x32_bf16 v[62:65], v[242:245], v[226:229], v[62:65]
	s_setprio 0
	s_waitcnt vmcnt(0)
	s_add_u32 s46, s46, 0x80
	s_addc_u32 s47, s47, 0
	s_addk_i32 s19, 0x2000
	s_cmpk_eq_i32 s46, 0x780
	s_waitcnt vmcnt(0)
	s_barrier
	s_cbranch_scc0 .LBB0_892
	s_andn2_b64 vcc, exec, s[44:45]
	s_cbranch_vccnz .LBB0_888
	v_lshl_add_u64 v[96:97], s[56:57], 1, v[66:67]
	v_readfirstlane_b32 s0, v113
	v_lshl_add_u64 v[98:99], v[96:97], 0, v[86:87]
	v_lshl_add_u64 v[104:105], s[52:53], 1, v[68:69]
	s_mov_b32 m0, s0
	v_readfirstlane_b32 s0, v114
	v_lshl_add_u64 v[106:107], v[104:105], 0, v[92:93]
	v_lshl_add_u64 v[108:109], v[104:105], 0, v[90:91]
	v_lshl_add_u64 v[110:111], v[104:105], 0, v[88:89]
	v_lshl_add_u64 v[104:105], v[104:105], 0, v[86:87]
	global_load_lds_dwordx4 v[98:99], off
	s_mov_b32 m0, s0
	v_readfirstlane_b32 s0, v115
	v_lshl_add_u64 v[100:101], v[96:97], 0, v[88:89]
	global_load_lds_dwordx4 v[104:105], off
	s_mov_b32 m0, s0
	v_readfirstlane_b32 s0, v116
	global_load_lds_dwordx4 v[100:101], off
	s_mov_b32 m0, s0
	v_readfirstlane_b32 s0, v117
	v_lshl_add_u64 v[102:103], v[96:97], 0, v[90:91]
	global_load_lds_dwordx4 v[110:111], off
	s_mov_b32 m0, s0
	v_readfirstlane_b32 s0, v118
	global_load_lds_dwordx4 v[102:103], off
	s_mov_b32 m0, s0
	v_readfirstlane_b32 s0, v119
	v_lshl_add_u64 v[96:97], v[96:97], 0, v[92:93]
	global_load_lds_dwordx4 v[108:109], off
	s_mov_b32 m0, s0
	v_readfirstlane_b32 s0, v120
	global_load_lds_dwordx4 v[96:97], off
	s_mov_b32 m0, s0
	s_nop 0
	global_load_lds_dwordx4 v[106:107], off
	s_branch .LBB0_888

.LBB0_1000:
	s_and_b32 s0, s33, 0x2000
	s_xor_b32 s1, s0, 0x2000
	s_lshl_b32 s0, s0, 1
	v_add_u32_e32 v0, s0, v123
	v_add_u32_e32 v129, s0, v124
	v_add_u32_e32 v142, v0, v127
	v_add_u32_e32 v158, v129, v127
	s_lshl_b32 s1, s1, 1
	v_readfirstlane_b32 s0, v250
	s_nop 0
	s_add_u32 m0, s0, s1
	ds_read_b128 v[130:133], v142
	global_load_lds_dwordx4 v246, s[98:99]
	s_add_u32 m0, m0, 0x8000
	ds_read_b128 v[134:137], v142 offset:2048
	global_load_lds_dwordx4 v246, s[100:101]
	s_add_u32 m0, m0, 0xffff8400
	ds_read_b128 v[138:141], v142 offset:4096
	global_load_lds_dwordx4 v247, s[98:99]
	s_add_u32 m0, m0, 0x8000
	ds_read_b128 v[142:145], v142 offset:6144
	global_load_lds_dwordx4 v247, s[100:101]
	s_add_u32 m0, m0, 0xffff8400
	ds_read_b128 v[146:149], v158 offset:32768
	global_load_lds_dwordx4 v248, s[98:99]
	s_add_u32 m0, m0, 0x8000
	ds_read_b128 v[150:153], v158 offset:34816
	global_load_lds_dwordx4 v248, s[100:101]
	s_add_u32 m0, m0, 0xffff8400
	ds_read_b128 v[154:157], v158 offset:36864
	global_load_lds_dwordx4 v249, s[98:99]
	s_add_u32 m0, m0, 0x8000
	ds_read_b128 v[158:161], v158 offset:38912
	global_load_lds_dwordx4 v249, s[100:101]
	v_add_u32_e32 v0, v0, v128
	ds_read_b128 v[214:217], v0
	ds_read_b128 v[218:221], v0 offset:2048
	ds_read_b128 v[222:225], v0 offset:4096
	ds_read_b128 v[226:229], v0 offset:6144
	v_add_u32_e32 v0, v129, v128
	ds_read_b128 v[230:233], v0 offset:32768
	ds_read_b128 v[234:237], v0 offset:34816
	ds_read_b128 v[238:241], v0 offset:36864
	s_setprio 1
	s_waitcnt lgkmcnt(7)
	ds_read_b128 v[242:245], v0 offset:38912
	s_add_u32 s98, s98, 0x80
	s_addc_u32 s99, s99, 0
	s_add_u32 s100, s100, 0x80
	s_addc_u32 s101, s101, 0
	v_mfma_f32_16x16x32_bf16 v[62:65], v[146:149], v[130:133], v[62:65]
	v_mfma_f32_16x16x32_bf16 v[58:61], v[150:153], v[130:133], v[58:61]
	v_mfma_f32_16x16x32_bf16 v[54:57], v[154:157], v[130:133], v[54:57]
	v_mfma_f32_16x16x32_bf16 v[50:53], v[158:161], v[130:133], v[50:53]
	v_mfma_f32_16x16x32_bf16 v[46:49], v[146:149], v[134:137], v[46:49]
	v_mfma_f32_16x16x32_bf16 v[42:45], v[150:153], v[134:137], v[42:45]
	v_mfma_f32_16x16x32_bf16 v[38:41], v[154:157], v[134:137], v[38:41]
	v_mfma_f32_16x16x32_bf16 v[34:37], v[158:161], v[134:137], v[34:37]
	v_mfma_f32_16x16x32_bf16 v[30:33], v[146:149], v[138:141], v[30:33]
	v_mfma_f32_16x16x32_bf16 v[26:29], v[150:153], v[138:141], v[26:29]
	v_mfma_f32_16x16x32_bf16 v[22:25], v[154:157], v[138:141], v[22:25]
	v_mfma_f32_16x16x32_bf16 v[18:21], v[158:161], v[138:141], v[18:21]
	v_mfma_f32_16x16x32_bf16 v[14:17], v[146:149], v[142:145], v[14:17]
	v_mfma_f32_16x16x32_bf16 v[10:13], v[150:153], v[142:145], v[10:13]
	v_mfma_f32_16x16x32_bf16 v[6:9], v[154:157], v[142:145], v[6:9]
	v_mfma_f32_16x16x32_bf16 v[2:5], v[158:161], v[142:145], v[2:5]
	s_waitcnt lgkmcnt(0)
	v_mfma_f32_16x16x32_bf16 v[62:65], v[230:233], v[214:217], v[62:65]
	v_mfma_f32_16x16x32_bf16 v[58:61], v[234:237], v[214:217], v[58:61]
	v_mfma_f32_16x16x32_bf16 v[54:57], v[238:241], v[214:217], v[54:57]
	v_mfma_f32_16x16x32_bf16 v[50:53], v[242:245], v[214:217], v[50:53]
	v_mfma_f32_16x16x32_bf16 v[46:49], v[230:233], v[218:221], v[46:49]
	v_mfma_f32_16x16x32_bf16 v[42:45], v[234:237], v[218:221], v[42:45]
	v_mfma_f32_16x16x32_bf16 v[38:41], v[238:241], v[218:221], v[38:41]
	v_mfma_f32_16x16x32_bf16 v[34:37], v[242:245], v[218:221], v[34:37]
	v_mfma_f32_16x16x32_bf16 v[30:33], v[230:233], v[222:225], v[30:33]
	v_mfma_f32_16x16x32_bf16 v[26:29], v[234:237], v[222:225], v[26:29]
	v_mfma_f32_16x16x32_bf16 v[22:25], v[238:241], v[222:225], v[22:25]
	v_mfma_f32_16x16x32_bf16 v[18:21], v[242:245], v[222:225], v[18:21]
	v_mfma_f32_16x16x32_bf16 v[14:17], v[230:233], v[226:229], v[14:17]
	v_mfma_f32_16x16x32_bf16 v[10:13], v[234:237], v[226:229], v[10:13]
	v_mfma_f32_16x16x32_bf16 v[6:9], v[238:241], v[226:229], v[6:9]
	v_mfma_f32_16x16x32_bf16 v[2:5], v[242:245], v[226:229], v[2:5]
	s_setprio 0
	s_addk_i32 s33, 0x2000
	s_waitcnt vmcnt(0)
	s_add_u32 s46, s46, 0x80
	s_addc_u32 s47, s47, 0
	s_cmpk_eq_i32 s46, 0x780
	s_waitcnt vmcnt(0)
	s_barrier
	s_cbranch_scc0 .LBB0_1000
	s_andn2_b64 vcc, exec, s[44:45]
	s_cbranch_vccnz .LBB0_996
	v_lshl_add_u64 v[94:95], v[66:67], 0, s[52:53]
	v_readfirstlane_b32 s0, v111
	v_lshl_add_u64 v[96:97], v[94:95], 0, v[86:87]
	v_lshl_add_u64 v[102:103], v[68:69], 0, s[56:57]
	s_mov_b32 m0, s0
	v_readfirstlane_b32 s0, v112
	v_lshl_add_u64 v[104:105], v[102:103], 0, v[92:93]
	v_lshl_add_u64 v[106:107], v[102:103], 0, v[90:91]
	v_lshl_add_u64 v[108:109], v[102:103], 0, v[88:89]
	v_lshl_add_u64 v[102:103], v[102:103], 0, v[86:87]
	global_load_lds_dwordx4 v[96:97], off
	s_mov_b32 m0, s0
	v_readfirstlane_b32 s0, v113
	v_lshl_add_u64 v[98:99], v[94:95], 0, v[88:89]
	global_load_lds_dwordx4 v[102:103], off
	s_mov_b32 m0, s0
	v_readfirstlane_b32 s0, v114
	global_load_lds_dwordx4 v[98:99], off
	s_mov_b32 m0, s0
	v_readfirstlane_b32 s0, v115
	v_lshl_add_u64 v[100:101], v[94:95], 0, v[90:91]
	global_load_lds_dwordx4 v[108:109], off
	s_mov_b32 m0, s0
	v_readfirstlane_b32 s0, v116
	global_load_lds_dwordx4 v[100:101], off
	s_mov_b32 m0, s0
	v_readfirstlane_b32 s0, v117
	v_lshl_add_u64 v[94:95], v[94:95], 0, v[92:93]
	global_load_lds_dwordx4 v[106:107], off
	s_mov_b32 m0, s0
	v_readfirstlane_b32 s0, v118
	global_load_lds_dwordx4 v[94:95], off
	s_mov_b32 m0, s0
	s_nop 0
	global_load_lds_dwordx4 v[104:105], off
	s_branch .LBB0_996

.LBB0_1058:
	s_and_b32 s0, s22, 0x2000
	s_xor_b32 s1, s0, 0x2000
	s_lshl_b32 s0, s0, 1
	v_add_u32_e32 v99, s0, v125
	v_add_u32_e32 v162, s0, v126
	v_add_u32_e32 v142, v99, v128
	v_add_u32_e32 v158, v162, v128
	s_lshl_b32 s1, s1, 1
	v_readfirstlane_b32 s0, v250
	s_nop 0
	s_add_u32 m0, s0, s1
	ds_read_b128 v[130:133], v142
	global_load_lds_dwordx4 v246, s[98:99]
	s_add_u32 m0, m0, 0x8000
	ds_read_b128 v[134:137], v142 offset:2048
	global_load_lds_dwordx4 v246, s[100:101]
	s_add_u32 m0, m0, 0xffff8400
	ds_read_b128 v[138:141], v142 offset:4096
	global_load_lds_dwordx4 v247, s[98:99]
	s_add_u32 m0, m0, 0x8000
	ds_read_b128 v[142:145], v142 offset:6144
	global_load_lds_dwordx4 v247, s[100:101]
	s_add_u32 m0, m0, 0xffff8400
	ds_read_b128 v[146:149], v158 offset:32768
	global_load_lds_dwordx4 v248, s[98:99]
	s_add_u32 m0, m0, 0x8000
	ds_read_b128 v[150:153], v158 offset:34816
	global_load_lds_dwordx4 v248, s[100:101]
	s_add_u32 m0, m0, 0xffff8400
	ds_read_b128 v[154:157], v158 offset:36864
	global_load_lds_dwordx4 v249, s[98:99]
	s_add_u32 m0, m0, 0x8000
	ds_read_b128 v[158:161], v158 offset:38912
	global_load_lds_dwordx4 v249, s[100:101]
	v_add_u32_e32 v99, v99, v129
	ds_read_b128 v[214:217], v99
	ds_read_b128 v[218:221], v99 offset:2048
	ds_read_b128 v[222:225], v99 offset:4096
	ds_read_b128 v[226:229], v99 offset:6144
	v_add_u32_e32 v99, v162, v129
	ds_read_b128 v[230:233], v99 offset:32768
	ds_read_b128 v[234:237], v99 offset:34816
	ds_read_b128 v[238:241], v99 offset:36864
	s_setprio 1
	s_waitcnt lgkmcnt(7)
	ds_read_b128 v[242:245], v99 offset:38912
	s_add_u32 s98, s98, 0x80
	s_addc_u32 s99, s99, 0
	s_add_u32 s100, s100, 0x80
	s_addc_u32 s101, s101, 0
	v_mfma_f32_16x16x32_bf16 v[2:5], v[146:149], v[130:133], v[2:5]
	v_mfma_f32_16x16x32_bf16 v[6:9], v[150:153], v[130:133], v[6:9]
	v_mfma_f32_16x16x32_bf16 v[10:13], v[154:157], v[130:133], v[10:13]
	v_mfma_f32_16x16x32_bf16 v[14:17], v[158:161], v[130:133], v[14:17]
	v_mfma_f32_16x16x32_bf16 v[18:21], v[146:149], v[134:137], v[18:21]
	v_mfma_f32_16x16x32_bf16 v[22:25], v[150:153], v[134:137], v[22:25]
	v_mfma_f32_16x16x32_bf16 v[26:29], v[154:157], v[134:137], v[26:29]
	v_mfma_f32_16x16x32_bf16 v[30:33], v[158:161], v[134:137], v[30:33]
	v_mfma_f32_16x16x32_bf16 v[34:37], v[146:149], v[138:141], v[34:37]
	v_mfma_f32_16x16x32_bf16 v[38:41], v[150:153], v[138:141], v[38:41]
	v_mfma_f32_16x16x32_bf16 v[42:45], v[154:157], v[138:141], v[42:45]
	v_mfma_f32_16x16x32_bf16 v[46:49], v[158:161], v[138:141], v[46:49]
	v_mfma_f32_16x16x32_bf16 v[50:53], v[146:149], v[142:145], v[50:53]
	v_mfma_f32_16x16x32_bf16 v[54:57], v[150:153], v[142:145], v[54:57]
	v_mfma_f32_16x16x32_bf16 v[58:61], v[154:157], v[142:145], v[58:61]
	v_mfma_f32_16x16x32_bf16 v[62:65], v[158:161], v[142:145], v[62:65]
	s_waitcnt lgkmcnt(0)
	v_mfma_f32_16x16x32_bf16 v[2:5], v[230:233], v[214:217], v[2:5]
	v_mfma_f32_16x16x32_bf16 v[6:9], v[234:237], v[214:217], v[6:9]
	v_mfma_f32_16x16x32_bf16 v[10:13], v[238:241], v[214:217], v[10:13]
	v_mfma_f32_16x16x32_bf16 v[14:17], v[242:245], v[214:217], v[14:17]
	v_mfma_f32_16x16x32_bf16 v[18:21], v[230:233], v[218:221], v[18:21]
	v_mfma_f32_16x16x32_bf16 v[22:25], v[234:237], v[218:221], v[22:25]
	v_mfma_f32_16x16x32_bf16 v[26:29], v[238:241], v[218:221], v[26:29]
	v_mfma_f32_16x16x32_bf16 v[30:33], v[242:245], v[218:221], v[30:33]
	v_mfma_f32_16x16x32_bf16 v[34:37], v[230:233], v[222:225], v[34:37]
	v_mfma_f32_16x16x32_bf16 v[38:41], v[234:237], v[222:225], v[38:41]
	v_mfma_f32_16x16x32_bf16 v[42:45], v[238:241], v[222:225], v[42:45]
	v_mfma_f32_16x16x32_bf16 v[46:49], v[242:245], v[222:225], v[46:49]
	v_mfma_f32_16x16x32_bf16 v[50:53], v[230:233], v[226:229], v[50:53]
	v_mfma_f32_16x16x32_bf16 v[54:57], v[234:237], v[226:229], v[54:57]
	v_mfma_f32_16x16x32_bf16 v[58:61], v[238:241], v[226:229], v[58:61]
	v_mfma_f32_16x16x32_bf16 v[62:65], v[242:245], v[226:229], v[62:65]
	s_setprio 0
	s_waitcnt vmcnt(0)
	s_add_u32 s42, s42, 0x80
	s_addc_u32 s43, s43, 0
	s_addk_i32 s22, 0x2000
	s_cmpk_eq_i32 s42, 0x1580
	s_waitcnt vmcnt(0)
	s_barrier
	s_cbranch_scc0 .LBB0_1058
	s_andn2_b64 vcc, exec, s[40:41]
	s_cbranch_vccnz .LBB0_1054
	v_lshl_add_u64 v[66:67], s[44:45], 1, v[78:79]
	v_readfirstlane_b32 s0, v113
	v_lshl_add_u64 v[68:69], v[66:67], 0, v[70:71]
	v_lshl_add_u64 v[104:105], s[46:47], 1, v[80:81]
	s_mov_b32 m0, s0
	v_readfirstlane_b32 s0, v114
	v_lshl_add_u64 v[106:107], v[104:105], 0, v[76:77]
	v_lshl_add_u64 v[108:109], v[104:105], 0, v[74:75]
	v_lshl_add_u64 v[110:111], v[104:105], 0, v[72:73]
	v_lshl_add_u64 v[104:105], v[104:105], 0, v[70:71]
	global_load_lds_dwordx4 v[68:69], off
	s_mov_b32 m0, s0
	v_readfirstlane_b32 s0, v115
	v_lshl_add_u64 v[100:101], v[66:67], 0, v[72:73]
	global_load_lds_dwordx4 v[104:105], off
	s_mov_b32 m0, s0
	v_readfirstlane_b32 s0, v116
	global_load_lds_dwordx4 v[100:101], off
	s_mov_b32 m0, s0
	v_readfirstlane_b32 s0, v117
	v_lshl_add_u64 v[102:103], v[66:67], 0, v[74:75]
	global_load_lds_dwordx4 v[110:111], off
	s_mov_b32 m0, s0
	v_readfirstlane_b32 s0, v118
	global_load_lds_dwordx4 v[102:103], off
	s_mov_b32 m0, s0
	v_readfirstlane_b32 s0, v119
	v_lshl_add_u64 v[66:67], v[66:67], 0, v[76:77]
	global_load_lds_dwordx4 v[108:109], off
	s_mov_b32 m0, s0
	v_readfirstlane_b32 s0, v120
	global_load_lds_dwordx4 v[66:67], off
	s_mov_b32 m0, s0
	s_nop 0
	global_load_lds_dwordx4 v[106:107], off
	s_branch .LBB0_1054
